# all seam / guard / unit-barrier flag polls without the s_sleep 1 back-off (s_nop 0), on step26
# baseline (speedup 1.0000x reference)
.LBB0_16:
	s_nop 0
	global_load_dword v2, v0, s[6:7] offset:32 sc1
	s_waitcnt vmcnt(0)
	v_and_b32_e32 v2, 0xffff0000, v2
	v_cmp_ne_u32_e32 vcc, v2, v1
	s_or_b64 s[8:9], vcc, s[8:9]
	s_andn2_b64 exec, exec, s[8:9]
	s_cbranch_execnz .LBB0_16

; __device__ __forceinline__ unsigned xb_ld(unsigned* p)              { return __hip_atomic_load(p, __ATOMIC_RELAXED, __HIP_MEMORY_SCOPE_AGENT); }
; __device__ __forceinline__ void xcd_barrier_complete(unsigned* bar, unsigned x, unsigned& nloc, unsigned& nx) {
;     const unsigned G = gridDim.x * gridDim.y * gridDim.z;
;     unsigned sum, cnt, mine, sp = 0u;
;     for (;;) {
;         sum = 0u; cnt = 0u; mine = 0u;
; #pragma unroll
;         for (unsigned j = 0; j < 16; ++j) { const unsigned c = xb_ld(&bar[XB_XCNT(j)]); sum += c; cnt += (c > 0u) ? 1u : 0u; mine = (j == x) ? c : mine; }
;         if (sum == G) break;
;         __builtin_amdgcn_s_sleep(1);
;         if ((++sp & 255u) == 0u) { if (xb_ld(&bar[XB_TMO])) break; if (sp > XB_SPIN_CAP) { atomicAdd(&bar[XB_TMO], 1u); break; } }
;     }
;     nloc = mine > 0u ? mine : 1u; nx = cnt > 0u ? cnt : 1u;
; }
.LBB0_167:
	global_load_dword v15, v16, s[14:15] sc1
	global_load_dword v0, v16, s[16:17] sc1
	global_load_dword v1, v16, s[18:19] sc1
	global_load_dword v2, v16, s[20:21] sc1
	global_load_dword v3, v16, s[22:23] sc1
	global_load_dword v4, v16, s[24:25] sc1
	global_load_dword v5, v16, s[26:27] sc1
	global_load_dword v6, v16, s[36:37] sc1
	global_load_dword v7, v16, s[40:41] sc1
	global_load_dword v8, v16, s[44:45] sc1
	global_load_dword v9, v16, s[48:49] sc1
	global_load_dword v10, v16, s[50:51] sc1
	global_load_dword v11, v16, s[52:53] sc1
	global_load_dword v12, v16, s[54:55] sc1
	global_load_dword v13, v16, s[56:57] sc1
	global_load_dword v14, v16, s[58:59] sc1
	s_mov_b64 s[60:61], -1
	s_mov_b64 s[62:63], -1
	s_waitcnt vmcnt(14)
	v_add_u32_e32 v17, v0, v15
	s_waitcnt vmcnt(13)
	v_add_u32_e32 v17, v17, v1
	s_waitcnt vmcnt(12)
	v_add_u32_e32 v17, v17, v2
	s_waitcnt vmcnt(11)
	v_add_u32_e32 v17, v17, v3
	s_waitcnt vmcnt(10)
	v_add_u32_e32 v17, v17, v4
	s_waitcnt vmcnt(9)
	v_add_u32_e32 v17, v17, v5
	s_waitcnt vmcnt(8)
	v_add_u32_e32 v17, v17, v6
	s_waitcnt vmcnt(7)
	v_add_u32_e32 v17, v17, v7
	s_waitcnt vmcnt(6)
	v_add_u32_e32 v17, v17, v8
	s_waitcnt vmcnt(5)
	v_add_u32_e32 v17, v17, v9
	s_waitcnt vmcnt(4)
	v_add_u32_e32 v17, v17, v10
	s_waitcnt vmcnt(3)
	v_add_u32_e32 v17, v17, v11
	s_waitcnt vmcnt(2)
	v_add_u32_e32 v17, v17, v12
	s_waitcnt vmcnt(1)
	v_add_u32_e32 v17, v17, v13
	s_waitcnt vmcnt(0)
	v_add_u32_e32 v17, v17, v14
	v_cmp_eq_u32_e32 vcc, s3, v17
	s_cbranch_vccnz .LBB0_166
	s_and_b32 s9, s8, 0xff
	s_cmp_eq_u32 s9, 0
	s_mov_b64 s[66:67], -1
	s_nop 0
	s_cbranch_scc0 .LBB0_171
	global_load_dword v17, v16, s[12:13] sc1
	s_waitcnt vmcnt(0)
	v_cmp_eq_u32_e32 vcc, 0, v17
	s_cbranch_vccnz .LBB0_173
	s_mov_b64 s[66:67], 0

; __device__ __forceinline__ unsigned xb_ld(unsigned* p)              { return __hip_atomic_load(p, __ATOMIC_RELAXED, __HIP_MEMORY_SCOPE_AGENT); }
; #define XB_SPIN(cond, bar) do { unsigned _sp = 0; while (cond) { __builtin_amdgcn_s_sleep(1); \
;     if ((++_sp & 255u) == 0u) { if (xb_ld(&(bar)[XB_TMO])) break; if (_sp > XB_SPIN_CAP) { atomicAdd(&(bar)[XB_TMO], 1u); break; } } } } while (0)
; __device__ __forceinline__ void xcd_barrier(const XcdBarrier& b) {
;     ...
;             else XB_SPIN(xb_ld(&bar[XB_TOPGEN]) == tg, bar);
.LBB0_183:
	s_and_b32 s8, s3, 0xff
	s_mov_b64 s[26:27], -1
	s_cmp_lg_u32 s8, 0
	s_mov_b64 s[40:41], -1
	s_nop 0
	s_cbranch_scc1 .LBB0_186
	global_load_dword v2, v0, s[18:19] sc1
	s_waitcnt vmcnt(0)
	v_cmp_eq_u32_e32 vcc, 0, v2
	s_cbranch_vccnz .LBB0_188
	s_mov_b64 s[40:41], 0
	s_mov_b64 s[36:37], -1

; __device__ __forceinline__ unsigned xb_ld(unsigned* p)              { return __hip_atomic_load(p, __ATOMIC_RELAXED, __HIP_MEMORY_SCOPE_AGENT); }
; #define XB_SPIN(cond, bar) do { unsigned _sp = 0; while (cond) { __builtin_amdgcn_s_sleep(1); \
;     if ((++_sp & 255u) == 0u) { if (xb_ld(&(bar)[XB_TMO])) break; if (_sp > XB_SPIN_CAP) { atomicAdd(&(bar)[XB_TMO], 1u); break; } } } } while (0)
; __device__ __forceinline__ void xcd_barrier(const XcdBarrier& b) {
;     ...
;             XB_SPIN(xb_ld(&bar[XB_XGEN(b.x)]) == gen, bar);
.LBB0_200:
	s_and_b32 s8, s3, 0xff
	s_cmp_lg_u32 s8, 0
	s_mov_b64 s[36:37], -1
	s_nop 0
	s_cbranch_scc1 .LBB0_203
	global_load_dword v1, v0, s[18:19] sc1
	s_waitcnt vmcnt(0)
	v_cmp_eq_u32_e32 vcc, 0, v1
	s_cbranch_vccnz .LBB0_205
	s_mov_b64 s[36:37], 0
	s_mov_b64 s[26:27], -1

.Ltb307_sspin:
	global_load_dword v3, v0, s[8:9] sc1
	s_waitcnt vmcnt(0)
	v_cmp_ge_u32_e32 vcc, v3, v2
	s_cbranch_vccnz .Ltb307_srel
	s_nop 0
	s_add_u32 s15, s15, 1
	s_cmp_lt_u32 s15, 0x400000
	s_cbranch_scc1 .Ltb307_sspin

.Llg519_spin:
	global_load_dword v253, v252, s[72:73] sc1
	s_waitcnt vmcnt(0)
	v_cmp_gt_u32_e32 vcc, s100, v253
	s_cmp_lg_u64 vcc, 0
	s_cbranch_scc0 .Llg519_wait
	s_nop 0
	s_add_u32 s101, s101, 1
	s_cmp_lt_u32 s101, 0x400000
	s_cbranch_scc1 .Llg519_spin
